# attention epilogue: gate rows requested at the epilogue start (duplicate early loads) so the real loads behind the O staging hit cache
# speedup vs baseline: 1.0079x; 1.0039x over previous
.Ltk_skip0:
	s_waitcnt lgkmcnt(0)
	ds_read_b128 v[32:35], v216 offset:49280
	ds_read_b128 v[36:39], v216 offset:49312
	s_lshl_b64 s[2:3], s[2:3], 12
	v_readlane_b32 s4, v252, 37
	s_add_u32 s5, s4, s2
	s_waitcnt lgkmcnt(1)
	v_rcp_f32_e32 v40, v32
	v_readlane_b32 s2, v252, 38
	s_addc_u32 s6, s2, s3
	s_lshl_b64 s[2:3], s[14:15], 1
	v_readlane_b32 s4, v252, 35
	v_rcp_f32_e32 v41, v33
	s_add_u32 s7, s4, s2
	v_readlane_b32 s2, v252, 36
	s_addc_u32 s14, s2, s3
	s_add_u32 s100, s7, s12
	s_addc_u32 s101, s14, 0
	v_lshlrev_b32_e32 v50, 1, v210
	v_and_b32_e32 v50, 0x70, v50
	v_mov_b32_e32 v51, 0
	v_lshrrev_b32_e32 v52, 3, v197
	v_lshl_add_u64 v[66:67], s[100:101], 0, v[50:51]
	v_or_b32_e32 v50, 0, v52
	v_lshlrev_b32_e32 v50, 11, v50
	v_lshl_add_u64 v[68:69], v[66:67], 0, v[50:51]
	global_load_dwordx4 v[70:73], v[68:69], off
	v_or_b32_e32 v50, 8, v52
	v_lshlrev_b32_e32 v50, 11, v50
	v_lshl_add_u64 v[68:69], v[66:67], 0, v[50:51]
	global_load_dwordx4 v[74:77], v[68:69], off
	v_or_b32_e32 v50, 16, v52
	v_lshlrev_b32_e32 v50, 11, v50
	v_lshl_add_u64 v[68:69], v[66:67], 0, v[50:51]
	global_load_dwordx4 v[78:81], v[68:69], off
	v_or_b32_e32 v50, 24, v52
	v_lshlrev_b32_e32 v50, 11, v50
	v_lshl_add_u64 v[68:69], v[66:67], 0, v[50:51]
	global_load_dwordx4 v[82:85], v[68:69], off
	s_lshl_b32 s2, s13, 12
	s_add_i32 s4, s2, 0
	v_lshlrev_b32_e32 v48, 1, v211
	v_lshlrev_b32_e32 v49, 9, v212
	v_mul_f32_e32 v0, v0, v40
	v_add3_u32 v48, s4, v48, v49
	v_cvt_pk_bf16_f32 v0, v0, s0
	v_rcp_f32_e32 v42, v34
	v_rcp_f32_e32 v43, v35
	s_waitcnt lgkmcnt(0)
	v_rcp_f32_e32 v44, v36
	ds_read_b128 v[32:35], v216 offset:49344
	v_rcp_f32_e32 v45, v37
	v_rcp_f32_e32 v46, v38
	v_rcp_f32_e32 v47, v39
	ds_read_b128 v[36:39], v216 offset:49376
	ds_write_b16 v48, v0 offset:51264
	v_mul_f32_e32 v0, v17, v41
	v_cvt_pk_bf16_f32 v0, v0, s0
	ds_write_b16 v48, v0 offset:51328
	v_mul_f32_e32 v0, v1, v41
	v_cvt_pk_bf16_f32 v0, v0, s0
	ds_write_b16 v48, v0 offset:51392
	v_mul_f32_e32 v0, v18, v42
	v_cvt_pk_bf16_f32 v0, v0, s0
	ds_write_b16 v48, v0 offset:51456
	v_mul_f32_e32 v0, v2, v42
	v_cvt_pk_bf16_f32 v0, v0, s0
	ds_write_b16 v48, v0 offset:51520
	v_mul_f32_e32 v0, v19, v43
	v_cvt_pk_bf16_f32 v0, v0, s0
	ds_write_b16 v48, v0 offset:51584
	v_mul_f32_e32 v0, v3, v43
	v_cvt_pk_bf16_f32 v0, v0, s0
	ds_write_b16 v48, v0 offset:51648
	v_mul_f32_e32 v0, v20, v44
	v_cvt_pk_bf16_f32 v0, v0, s0
	ds_write_b16 v48, v0 offset:52224
	v_mul_f32_e32 v0, v4, v44
	v_cvt_pk_bf16_f32 v0, v0, s0
	ds_write_b16 v48, v0 offset:52288
	v_mul_f32_e32 v0, v21, v45
	v_cvt_pk_bf16_f32 v0, v0, s0
	ds_write_b16 v48, v0 offset:52352
	v_mul_f32_e32 v0, v5, v45
	v_cvt_pk_bf16_f32 v0, v0, s0
	ds_write_b16 v48, v0 offset:52416
	v_mul_f32_e32 v0, v22, v46
	v_cvt_pk_bf16_f32 v0, v0, s0
	ds_write_b16 v48, v0 offset:52480
	v_mul_f32_e32 v0, v6, v46
	v_cvt_pk_bf16_f32 v0, v0, s0
	s_waitcnt lgkmcnt(13)
	v_rcp_f32_e32 v32, v32
	ds_write_b16 v48, v0 offset:52544
	v_mul_f32_e32 v0, v23, v47
	v_cvt_pk_bf16_f32 v0, v0, s0
	ds_write_b16 v48, v0 offset:52608
	v_mul_f32_e32 v0, v7, v47
	v_cvt_pk_bf16_f32 v0, v0, s0
	v_rcp_f32_e32 v33, v33
	ds_write_b16 v48, v0 offset:52672
	v_mul_f32_e32 v0, v24, v32
	v_cvt_pk_bf16_f32 v0, v0, s0
	ds_write_b16 v48, v0 offset:53248
	v_mul_f32_e32 v0, v8, v32
	v_cvt_pk_bf16_f32 v0, v0, s0
	v_rcp_f32_e32 v34, v34
	ds_write_b16 v48, v0 offset:53312
	v_mul_f32_e32 v0, v25, v33
	v_cvt_pk_bf16_f32 v0, v0, s0
	ds_write_b16 v48, v0 offset:53376
	v_mul_f32_e32 v0, v9, v33
	v_cvt_pk_bf16_f32 v0, v0, s0
	v_rcp_f32_e32 v35, v35
	ds_write_b16 v48, v0 offset:53440
	v_mul_f32_e32 v0, v26, v34
	v_cvt_pk_bf16_f32 v0, v0, s0
	ds_write_b16 v48, v0 offset:53504
	v_mul_f32_e32 v0, v10, v34
	v_cvt_pk_bf16_f32 v0, v0, s0
	s_waitcnt lgkmcnt(14)
	v_rcp_f32_e32 v36, v36
	ds_write_b16 v48, v0 offset:53568
	v_mul_f32_e32 v0, v27, v35
	v_cvt_pk_bf16_f32 v0, v0, s0
	ds_write_b16 v48, v0 offset:53632
	v_mul_f32_e32 v0, v11, v35
	v_cvt_pk_bf16_f32 v0, v0, s0
	v_rcp_f32_e32 v37, v37
	ds_write_b16 v48, v0 offset:53696
	v_mul_f32_e32 v0, v28, v36
	v_cvt_pk_bf16_f32 v0, v0, s0
	ds_write_b16 v48, v0 offset:54272
	v_mul_f32_e32 v0, v12, v36
	v_cvt_pk_bf16_f32 v0, v0, s0
	v_rcp_f32_e32 v38, v38
	ds_write_b16 v48, v0 offset:54336
	v_mul_f32_e32 v0, v29, v37
	v_cvt_pk_bf16_f32 v0, v0, s0
	ds_write_b16 v48, v0 offset:54400
	v_mul_f32_e32 v0, v13, v37
	v_cvt_pk_bf16_f32 v0, v0, s0
	v_rcp_f32_e32 v39, v39
	ds_write_b16 v48, v0 offset:54464
	v_mul_f32_e32 v0, v30, v38
	v_cvt_pk_bf16_f32 v0, v0, s0
	ds_write_b16 v48, v0 offset:54528
	v_mul_f32_e32 v0, v14, v38
	v_cvt_pk_bf16_f32 v0, v0, s0
	ds_write_b16 v48, v0 offset:54592
	v_mul_f32_e32 v0, v31, v39
	v_cvt_pk_bf16_f32 v0, v0, s0
	ds_write_b16 v48, v0 offset:54656
	v_mul_f32_e32 v0, v15, v39
	s_add_u32 s2, s5, s12
	v_mul_f32_e32 v16, v16, v40
	v_cvt_pk_bf16_f32 v0, v0, s0
	s_addc_u32 s3, s6, 0
	v_cvt_pk_bf16_f32 v16, v16, s0
	ds_write_b16 v48, v0 offset:54720
	s_add_u32 s6, s7, s12
	v_lshlrev_b32_e32 v0, 1, v210
	ds_write_b16 v48, v16 offset:51200
	s_addc_u32 s7, s14, 0
	v_lshrrev_b32_e32 v24, 3, v197
	v_and_b32_e32 v16, 0x70, v0
	v_mov_b32_e32 v17, v193
	v_lshl_add_u64 v[18:19], s[6:7], 0, v[16:17]
	v_lshlrev_b32_e32 v0, 11, v24
	v_mov_b32_e32 v1, v193
	s_waitcnt lgkmcnt(0)
	v_lshl_add_u64 v[0:1], v[18:19], 0, v[0:1]
	global_load_dwordx4 v[0:3], v[0:1], off
	v_or_b32_e32 v25, 8, v24
	v_lshlrev_b32_e32 v4, 11, v25
	v_mov_b32_e32 v5, v193
	v_lshl_add_u64 v[4:5], v[18:19], 0, v[4:5]
	global_load_dwordx4 v[4:7], v[4:5], off
	v_or_b32_e32 v26, 16, v24
	v_lshlrev_b32_e32 v8, 11, v26
	v_mov_b32_e32 v9, v193
	v_lshl_add_u64 v[8:9], v[18:19], 0, v[8:9]
	global_load_dwordx4 v[8:11], v[8:9], off
	v_add_u32_e32 v27, s4, v16
	v_lshl_add_u32 v12, v24, 7, v27
	ds_read_b128 v[12:15], v12 offset:51200
	v_lshl_add_u64 v[20:21], s[2:3], 0, v[16:17]
	v_or_b32_e32 v28, 24, v24
	s_waitcnt lgkmcnt(0)
	v_lshlrev_b32_e32 v16, 16, v12
	v_and_b32_e32 v17, 0xffff0000, v12
	v_lshlrev_b32_e32 v12, 16, v13
	v_and_b32_e32 v13, 0xffff0000, v13
	s_waitcnt vmcnt(2)
	v_lshlrev_b32_e32 v22, 16, v0
	v_and_b32_e32 v23, 0xffff0000, v0
	v_pk_mul_f32 v[16:17], v[16:17], v[22:23]
	v_lshlrev_b32_e32 v22, 16, v2
	v_cvt_pk_bf16_f32 v0, v16, v17
	v_lshlrev_b32_e32 v16, 16, v1
	v_and_b32_e32 v17, 0xffff0000, v1
	v_pk_mul_f32 v[12:13], v[12:13], v[16:17]
	v_lshlrev_b32_e32 v16, 11, v28
	v_mov_b32_e32 v17, v193
	v_lshl_add_u64 v[16:17], v[18:19], 0, v[16:17]
	global_load_dwordx4 v[16:19], v[16:17], off
	v_cvt_pk_bf16_f32 v1, v12, v13
	v_lshlrev_b32_e32 v12, 16, v14
	v_and_b32_e32 v13, 0xffff0000, v14
	v_and_b32_e32 v23, 0xffff0000, v2
	v_pk_mul_f32 v[12:13], v[12:13], v[22:23]
	v_lshlrev_b32_e32 v14, 16, v3
	v_cvt_pk_bf16_f32 v2, v12, v13
	v_lshlrev_b32_e32 v12, 16, v15
	v_and_b32_e32 v13, 0xffff0000, v15
	v_and_b32_e32 v15, 0xffff0000, v3
	v_pk_mul_f32 v[12:13], v[12:13], v[14:15]
	v_lshlrev_b32_e32 v22, 12, v24
	v_cvt_pk_bf16_f32 v3, v12, v13
	v_lshl_add_u32 v12, v25, 7, v27
	ds_read_b128 v[12:15], v12 offset:51200
	v_mov_b32_e32 v23, v193
	v_lshl_add_u64 v[22:23], v[20:21], 0, v[22:23]
	global_store_dwordx4 v[22:23], v[0:3], off
	s_waitcnt lgkmcnt(0)
	s_nop 0
	v_lshlrev_b32_e32 v0, 16, v12
	v_and_b32_e32 v1, 0xffff0000, v12
	s_waitcnt vmcnt(3)
	v_lshlrev_b32_e32 v2, 16, v4
	v_and_b32_e32 v3, 0xffff0000, v4
	v_pk_mul_f32 v[0:1], v[0:1], v[2:3]
	v_lshlrev_b32_e32 v2, 16, v13
	v_and_b32_e32 v3, 0xffff0000, v13
	v_lshlrev_b32_e32 v4, 16, v5
	v_and_b32_e32 v5, 0xffff0000, v5
	v_pk_mul_f32 v[2:3], v[2:3], v[4:5]
	v_cvt_pk_bf16_f32 v0, v0, v1
	v_cvt_pk_bf16_f32 v1, v2, v3
	v_lshlrev_b32_e32 v2, 16, v14
	v_and_b32_e32 v3, 0xffff0000, v14
	v_lshlrev_b32_e32 v4, 16, v6
	v_and_b32_e32 v5, 0xffff0000, v6
	v_pk_mul_f32 v[2:3], v[2:3], v[4:5]
	v_lshlrev_b32_e32 v4, 16, v15
	v_and_b32_e32 v5, 0xffff0000, v15
	v_lshlrev_b32_e32 v6, 16, v7
	v_and_b32_e32 v7, 0xffff0000, v7
	v_pk_mul_f32 v[4:5], v[4:5], v[6:7]
	v_cvt_pk_bf16_f32 v2, v2, v3
	v_cvt_pk_bf16_f32 v3, v4, v5
	v_lshl_add_u32 v4, v26, 7, v27
	ds_read_b128 v[4:7], v4 offset:51200
	v_lshlrev_b32_e32 v12, 12, v25
	v_mov_b32_e32 v13, v193
	v_lshl_add_u64 v[12:13], v[20:21], 0, v[12:13]
	global_store_dwordx4 v[12:13], v[0:3], off
	s_waitcnt lgkmcnt(0)
	s_nop 0
	v_lshlrev_b32_e32 v0, 16, v4
	v_and_b32_e32 v1, 0xffff0000, v4
	s_waitcnt vmcnt(3)
	v_lshlrev_b32_e32 v2, 16, v8
	v_and_b32_e32 v3, 0xffff0000, v8
	v_pk_mul_f32 v[0:1], v[0:1], v[2:3]
	v_lshlrev_b32_e32 v2, 16, v5
	v_and_b32_e32 v3, 0xffff0000, v5
	v_lshlrev_b32_e32 v4, 16, v9
	v_and_b32_e32 v5, 0xffff0000, v9
	v_pk_mul_f32 v[2:3], v[2:3], v[4:5]
	v_cvt_pk_bf16_f32 v0, v0, v1
	v_cvt_pk_bf16_f32 v1, v2, v3
	v_lshlrev_b32_e32 v2, 16, v6
	v_and_b32_e32 v3, 0xffff0000, v6
	v_lshlrev_b32_e32 v4, 16, v10
	v_and_b32_e32 v5, 0xffff0000, v10
	v_pk_mul_f32 v[2:3], v[2:3], v[4:5]
	v_lshlrev_b32_e32 v4, 16, v7
	v_and_b32_e32 v5, 0xffff0000, v7
	v_lshlrev_b32_e32 v6, 16, v11
	v_and_b32_e32 v7, 0xffff0000, v11
	v_pk_mul_f32 v[4:5], v[4:5], v[6:7]
	v_cvt_pk_bf16_f32 v2, v2, v3
	v_cvt_pk_bf16_f32 v3, v4, v5
	v_lshl_add_u32 v4, v28, 7, v27
	ds_read_b128 v[4:7], v4 offset:51200
	v_lshlrev_b32_e32 v8, 12, v26
	v_mov_b32_e32 v9, v193
	v_lshl_add_u64 v[8:9], v[20:21], 0, v[8:9]
	global_store_dwordx4 v[8:9], v[0:3], off
	s_waitcnt lgkmcnt(0)
	s_nop 0
	v_lshlrev_b32_e32 v0, 16, v4
	v_and_b32_e32 v1, 0xffff0000, v4
	s_waitcnt vmcnt(3)
	v_lshlrev_b32_e32 v2, 16, v16
	v_and_b32_e32 v3, 0xffff0000, v16
	v_pk_mul_f32 v[0:1], v[0:1], v[2:3]
	v_lshlrev_b32_e32 v2, 16, v5
	v_and_b32_e32 v3, 0xffff0000, v5
	v_lshlrev_b32_e32 v4, 16, v17
	v_and_b32_e32 v5, 0xffff0000, v17
	v_pk_mul_f32 v[2:3], v[2:3], v[4:5]
	v_cvt_pk_bf16_f32 v0, v0, v1
	v_cvt_pk_bf16_f32 v1, v2, v3
	v_lshlrev_b32_e32 v2, 16, v6
	v_and_b32_e32 v3, 0xffff0000, v6
	v_lshlrev_b32_e32 v4, 16, v18
	v_and_b32_e32 v5, 0xffff0000, v18
	v_pk_mul_f32 v[2:3], v[2:3], v[4:5]
	v_lshlrev_b32_e32 v4, 16, v7
	v_and_b32_e32 v5, 0xffff0000, v7
	v_lshlrev_b32_e32 v6, 16, v19
	v_and_b32_e32 v7, 0xffff0000, v19
	v_pk_mul_f32 v[4:5], v[4:5], v[6:7]
	v_cvt_pk_bf16_f32 v2, v2, v3
	v_cvt_pk_bf16_f32 v3, v4, v5
	v_lshlrev_b32_e32 v4, 12, v28
	v_mov_b32_e32 v5, v193
	v_lshl_add_u64 v[4:5], v[20:21], 0, v[4:5]
	global_store_dwordx4 v[4:5], v[0:3], off
	s_cmp_lg_u32 s13, 0
	s_cbranch_scc1 .Ltk_skip1
	s_waitcnt vmcnt(4)
	v_readfirstlane_b32 s4, v96
	s_nop 3
	s_add_i32 s4, s4, s65
	s_mov_b64 s[6:7], exec
	s_mov_b64 exec, 1
	v_mov_b32_e32 v96, s4
	v_mov_b32_e32 v97, s68
	ds_write_b32 v97, v96
	s_mov_b64 exec, s[6:7]
